# adds: attention cross-half row-max exchange via v_permlane32_swap instead of ds_bpermute round trip
# speedup vs baseline: 1.0114x; 1.0008x over previous
.LBB0_190:
	s_nop 8
	v_max_f32_e32 v2, v83, v83
	v_max_f32_e32 v4, v82, v82
	v_max_f32_e32 v2, v4, v2
	v_max3_f32 v4, v84, v85, v67
	v_max3_f32 v2, v2, v66, v68
	v_max3_f32 v2, v2, v69, v86
	v_max3_f32 v4, v4, v88, v89
	v_max3_f32 v2, v2, v87, v70
	v_max3_f32 v4, v4, v72, v73
	v_max3_f32 v2, v2, v71, v90
	v_max3_f32 v4, v4, v92, v93
	v_max3_f32 v2, v2, v91, v74
	v_max3_f32 v4, v4, v76, v77
	v_max3_f32 v2, v2, v75, v94
	v_max3_f32 v4, v4, v96, v97
	v_max3_f32 v2, v2, v95, v78
	v_max3_f32 v4, v4, v80, v81
	v_max3_f32 v2, v2, v79, v4
	v_mov_b32_e32 v4, v2
	s_nop 1
	v_permlane32_swap_b32_e32 v4, v2
	s_mov_b32 s2, 0x41000000
	s_waitcnt lgkmcnt(0)
	v_max_f32_e32 v4, v4, v4
	v_max_f32_e32 v2, v2, v4
	v_cmp_lt_f32_e32 vcc, s2, v2
	s_cbranch_vccz .LBB0_192
	s_nop 0
	v_cndmask_b32_e32 v2, 0, v2, vcc
	v_exp_f32_e64 v4, -v2
	v_add_f32_e32 v182, v182, v2
	v_xor_b32_e32 v50, 0x80000000, v182
	v_pk_add_f32 v[82:83], v[82:83], v[2:3] op_sel_hi:[1,0] neg_lo:[0,1] neg_hi:[0,1]
	v_pk_add_f32 v[66:67], v[66:67], v[2:3] op_sel_hi:[1,0] neg_lo:[0,1] neg_hi:[0,1]
	v_pk_add_f32 v[84:85], v[84:85], v[2:3] op_sel_hi:[1,0] neg_lo:[0,1] neg_hi:[0,1]
	v_pk_add_f32 v[68:69], v[68:69], v[2:3] op_sel_hi:[1,0] neg_lo:[0,1] neg_hi:[0,1]
	v_pk_add_f32 v[86:87], v[86:87], v[2:3] op_sel_hi:[1,0] neg_lo:[0,1] neg_hi:[0,1]
	v_pk_add_f32 v[70:71], v[70:71], v[2:3] op_sel_hi:[1,0] neg_lo:[0,1] neg_hi:[0,1]
	v_pk_add_f32 v[88:89], v[88:89], v[2:3] op_sel_hi:[1,0] neg_lo:[0,1] neg_hi:[0,1]
	v_pk_add_f32 v[72:73], v[72:73], v[2:3] op_sel_hi:[1,0] neg_lo:[0,1] neg_hi:[0,1]
	v_pk_add_f32 v[90:91], v[90:91], v[2:3] op_sel_hi:[1,0] neg_lo:[0,1] neg_hi:[0,1]
	v_pk_add_f32 v[74:75], v[74:75], v[2:3] op_sel_hi:[1,0] neg_lo:[0,1] neg_hi:[0,1]
	v_pk_add_f32 v[92:93], v[92:93], v[2:3] op_sel_hi:[1,0] neg_lo:[0,1] neg_hi:[0,1]
	v_pk_add_f32 v[76:77], v[76:77], v[2:3] op_sel_hi:[1,0] neg_lo:[0,1] neg_hi:[0,1]
	v_pk_add_f32 v[94:95], v[94:95], v[2:3] op_sel_hi:[1,0] neg_lo:[0,1] neg_hi:[0,1]
	v_pk_add_f32 v[78:79], v[78:79], v[2:3] op_sel_hi:[1,0] neg_lo:[0,1] neg_hi:[0,1]
	v_pk_mul_f32 v[32:33], v[32:33], v[4:5] op_sel_hi:[1,0]
	v_pk_mul_f32 v[30:31], v[30:31], v[4:5] op_sel_hi:[1,0]
	v_pk_mul_f32 v[28:29], v[28:29], v[4:5] op_sel_hi:[1,0]
	v_pk_mul_f32 v[26:27], v[26:27], v[4:5] op_sel_hi:[1,0]
	v_pk_mul_f32 v[24:25], v[24:25], v[4:5] op_sel_hi:[1,0]
	v_pk_mul_f32 v[22:23], v[22:23], v[4:5] op_sel_hi:[1,0]
	v_pk_mul_f32 v[20:21], v[20:21], v[4:5] op_sel_hi:[1,0]
	v_pk_mul_f32 v[18:19], v[18:19], v[4:5] op_sel_hi:[1,0]
	v_pk_mul_f32 v[48:49], v[48:49], v[4:5] op_sel_hi:[1,0]
	v_pk_mul_f32 v[46:47], v[46:47], v[4:5] op_sel_hi:[1,0]
	v_pk_mul_f32 v[44:45], v[44:45], v[4:5] op_sel_hi:[1,0]
	v_pk_mul_f32 v[42:43], v[42:43], v[4:5] op_sel_hi:[1,0]
	v_pk_mul_f32 v[40:41], v[40:41], v[4:5] op_sel_hi:[1,0]
	v_pk_mul_f32 v[38:39], v[38:39], v[4:5] op_sel_hi:[1,0]
	v_pk_mul_f32 v[36:37], v[36:37], v[4:5] op_sel_hi:[1,0]
	v_pk_mul_f32 v[34:35], v[34:35], v[4:5] op_sel_hi:[1,0]
	v_pk_add_f32 v[96:97], v[96:97], v[2:3] op_sel_hi:[1,0] neg_lo:[0,1] neg_hi:[0,1]
	v_pk_add_f32 v[80:81], v[80:81], v[2:3] op_sel_hi:[1,0] neg_lo:[0,1] neg_hi:[0,1]
	v_mul_f32_e32 v5, v5, v4
	v_mov_b32_e32 v51, v50
	v_mov_b32_e32 v52, v50
	v_mov_b32_e32 v53, v50
	v_mov_b32_e32 v54, v50
	v_mov_b32_e32 v55, v50
	v_mov_b32_e32 v56, v50
	v_mov_b32_e32 v57, v50
	v_mov_b32_e32 v58, v50
	v_mov_b32_e32 v59, v50
	v_mov_b32_e32 v60, v50
	v_mov_b32_e32 v61, v50
	v_mov_b32_e32 v62, v50
	v_mov_b32_e32 v63, v50
	v_mov_b32_e32 v64, v50
	v_mov_b32_e32 v65, v50

.LBB0_284:
	s_nop 8
	v_max_f32_e32 v2, v83, v83
	v_max_f32_e32 v4, v82, v82
	v_max_f32_e32 v2, v4, v2
	v_max3_f32 v4, v84, v85, v67
	v_max3_f32 v2, v2, v66, v68
	v_max3_f32 v2, v2, v69, v86
	v_max3_f32 v4, v4, v88, v89
	v_max3_f32 v2, v2, v87, v70
	v_max3_f32 v4, v4, v72, v73
	v_max3_f32 v2, v2, v71, v90
	v_max3_f32 v4, v4, v92, v93
	v_max3_f32 v2, v2, v91, v74
	v_max3_f32 v4, v4, v76, v77
	v_max3_f32 v2, v2, v75, v94
	v_max3_f32 v4, v4, v96, v97
	v_max3_f32 v2, v2, v95, v78
	v_max3_f32 v4, v4, v80, v81
	v_max3_f32 v2, v2, v79, v4
	v_mov_b32_e32 v4, v2
	s_nop 1
	v_permlane32_swap_b32_e32 v4, v2
	s_mov_b32 s3, 0x41000000
	s_waitcnt lgkmcnt(0)
	v_max_f32_e32 v4, v4, v4
	v_max_f32_e32 v2, v2, v4
	v_cmp_lt_f32_e32 vcc, s3, v2
	s_cbranch_vccz .LBB0_286
	s_nop 0
	v_cndmask_b32_e32 v2, 0, v2, vcc
	v_exp_f32_e64 v4, -v2
	v_add_f32_e32 v200, v200, v2
	v_xor_b32_e32 v50, 0x80000000, v200
	v_pk_add_f32 v[82:83], v[82:83], v[2:3] op_sel_hi:[1,0] neg_lo:[0,1] neg_hi:[0,1]
	v_pk_add_f32 v[66:67], v[66:67], v[2:3] op_sel_hi:[1,0] neg_lo:[0,1] neg_hi:[0,1]
	v_pk_add_f32 v[84:85], v[84:85], v[2:3] op_sel_hi:[1,0] neg_lo:[0,1] neg_hi:[0,1]
	v_pk_add_f32 v[68:69], v[68:69], v[2:3] op_sel_hi:[1,0] neg_lo:[0,1] neg_hi:[0,1]
	v_pk_add_f32 v[86:87], v[86:87], v[2:3] op_sel_hi:[1,0] neg_lo:[0,1] neg_hi:[0,1]
	v_pk_add_f32 v[70:71], v[70:71], v[2:3] op_sel_hi:[1,0] neg_lo:[0,1] neg_hi:[0,1]
	v_pk_add_f32 v[88:89], v[88:89], v[2:3] op_sel_hi:[1,0] neg_lo:[0,1] neg_hi:[0,1]
	v_pk_add_f32 v[72:73], v[72:73], v[2:3] op_sel_hi:[1,0] neg_lo:[0,1] neg_hi:[0,1]
	v_pk_add_f32 v[90:91], v[90:91], v[2:3] op_sel_hi:[1,0] neg_lo:[0,1] neg_hi:[0,1]
	v_pk_add_f32 v[74:75], v[74:75], v[2:3] op_sel_hi:[1,0] neg_lo:[0,1] neg_hi:[0,1]
	v_pk_add_f32 v[92:93], v[92:93], v[2:3] op_sel_hi:[1,0] neg_lo:[0,1] neg_hi:[0,1]
	v_pk_add_f32 v[76:77], v[76:77], v[2:3] op_sel_hi:[1,0] neg_lo:[0,1] neg_hi:[0,1]
	v_pk_add_f32 v[94:95], v[94:95], v[2:3] op_sel_hi:[1,0] neg_lo:[0,1] neg_hi:[0,1]
	v_pk_add_f32 v[78:79], v[78:79], v[2:3] op_sel_hi:[1,0] neg_lo:[0,1] neg_hi:[0,1]
	v_pk_mul_f32 v[32:33], v[32:33], v[4:5] op_sel_hi:[1,0]
	v_pk_mul_f32 v[30:31], v[30:31], v[4:5] op_sel_hi:[1,0]
	v_pk_mul_f32 v[28:29], v[28:29], v[4:5] op_sel_hi:[1,0]
	v_pk_mul_f32 v[26:27], v[26:27], v[4:5] op_sel_hi:[1,0]
	v_pk_mul_f32 v[24:25], v[24:25], v[4:5] op_sel_hi:[1,0]
	v_pk_mul_f32 v[22:23], v[22:23], v[4:5] op_sel_hi:[1,0]
	v_pk_mul_f32 v[20:21], v[20:21], v[4:5] op_sel_hi:[1,0]
	v_pk_mul_f32 v[18:19], v[18:19], v[4:5] op_sel_hi:[1,0]
	v_pk_mul_f32 v[48:49], v[48:49], v[4:5] op_sel_hi:[1,0]
	v_pk_mul_f32 v[46:47], v[46:47], v[4:5] op_sel_hi:[1,0]
	v_pk_mul_f32 v[44:45], v[44:45], v[4:5] op_sel_hi:[1,0]
	v_pk_mul_f32 v[42:43], v[42:43], v[4:5] op_sel_hi:[1,0]
	v_pk_mul_f32 v[40:41], v[40:41], v[4:5] op_sel_hi:[1,0]
	v_pk_mul_f32 v[38:39], v[38:39], v[4:5] op_sel_hi:[1,0]
	v_pk_mul_f32 v[36:37], v[36:37], v[4:5] op_sel_hi:[1,0]
	v_pk_mul_f32 v[34:35], v[34:35], v[4:5] op_sel_hi:[1,0]
	v_pk_add_f32 v[96:97], v[96:97], v[2:3] op_sel_hi:[1,0] neg_lo:[0,1] neg_hi:[0,1]
	v_pk_add_f32 v[80:81], v[80:81], v[2:3] op_sel_hi:[1,0] neg_lo:[0,1] neg_hi:[0,1]
	v_mul_f32_e32 v5, v5, v4
	v_mov_b32_e32 v51, v50
	v_mov_b32_e32 v52, v50
	v_mov_b32_e32 v53, v50
	v_mov_b32_e32 v54, v50
	v_mov_b32_e32 v55, v50
	v_mov_b32_e32 v56, v50
	v_mov_b32_e32 v57, v50
	v_mov_b32_e32 v58, v50
	v_mov_b32_e32 v59, v50
	v_mov_b32_e32 v60, v50
	v_mov_b32_e32 v61, v50
	v_mov_b32_e32 v62, v50
	v_mov_b32_e32 v63, v50
	v_mov_b32_e32 v64, v50
	v_mov_b32_e32 v65, v50
